# PV: initial burst of 8 transposed V reads split 4 + max chain + 4 (need-ordered)
# baseline (speedup 1.0000x reference)
; #define SBAR() __builtin_amdgcn_sched_barrier(0)
; #define KWRITE(b, src0, src1) do { if constexpr (ND0 == 4) { *(bf16x8*)(K_lds + (b) * SHM_K + KSWZ(kr, kcb)) = src0; } \
;     else { int kc = sc * 2; *(bf16x8*)(K_lds + (b) * SHM_K + KSWZ(sr, kc)) = src0; *(bf16x8*)(K_lds + (b) * SHM_K + KSWZ(32 + sr, kc)) = src1; } } while (0)
; #define SLOAD_B(k0) do { vs0b = *reinterpret_cast<const bf16x8*>(&Vh[(long)((k0) + sr) * LDK + sc]); vs1b = *reinterpret_cast<const bf16x8*>(&Vh[(long)((k0) + 32 + sr) * LDK + sc]); KLOAD(ks0b, ks1b, k0); } while (0)
; #define PSM(P0, P1, MN, AL) do { if constexpr (PRE) partialSM_pre(P0, P1, m_reg, AL, 11.541560327111707f); else partialSM(P0, P1, m_reg, MN, AL, C, thr_raw); } while (0)
; __device__ __forceinline__ void finishSM(f32x16& p0, f32x16& p1, float alpha, float& l_reg, bf16x8& pa0, bf16x8& pa1, bf16x8& pa2, bf16x8& pa3) {
; #pragma unroll
;   for (int r = 0; r < 16; ++r) p1[r] = __builtin_amdgcn_exp2f(p1[r]);
;   float ps = 0;
; #pragma unroll
;   for (int r = 0; r < 16; ++r) ps += p0[r];
; #pragma unroll
;   for (int r = 0; r < 16; ++r) ps += p1[r];
;   { auto rr = __builtin_amdgcn_permlane32_swap(__float_as_uint(ps), __float_as_uint(ps), false, false);
;     ps = __uint_as_float(rr[0]) + __uint_as_float(rr[1]); }
;   l_reg = l_reg * alpha + ps;
;     ...
;   PK4(p0, 0, pa0); PK4(p0, 8, pa1); PK4(p1, 0, pa2); PK4(p1, 8, pa3);
;     ...
; }
; template <int ND0>
; __device__ __forceinline__ void qkt(f32x16& p0, f32x16& p1, const char* Ks, const bf16x8* qr, int r32, int hi) {
;   p0 = f32x16{}; p1 = f32x16{};
; #pragma unroll
;   for (int d0 = 0; d0 < ND0; ++d0) { int cb = (d0 * 16 + hi * 8) * 2;
;     bf16x8 b0 = *reinterpret_cast<const bf16x8*>(Ks + KSWZ(r32, cb));
;     bf16x8 b1 = *reinterpret_cast<const bf16x8*>(Ks + KSWZ(32 + r32, cb));
;     p0 = __builtin_amdgcn_mfma_f32_32x32x16_bf16(b0, qr[d0], p0, 0, 0, 0);
;     p1 = __builtin_amdgcn_mfma_f32_32x32x16_bf16(b1, qr[d0], p1, 0, 0, 0); }
; }
; template <int ND0, int LDQ, int LDK, int LDO> ...
;     ...
;     SBAR(); qkt<ND0>(pB0, pB1, Kq1, qr, r32, hi);
;     finishSM(pA0, pA1, alA, l_reg, pa0, pa1, pa2, pa3); SBAR();
;     SLOAD_B((j + 2) * KVBLK); SBAR();
;     pv_d0(o, vb0, pa0, pa1, pa2, pa3); KWRITE(0, ks0a, ks1a); PSM(pB0, pB1, mnB, alB);
.LBB0_146:
	v_exp_f32_e32 v170, v64
	s_waitcnt lgkmcnt(0)
	v_mfma_f32_32x32x16_bf16 v[96:111], v[80:83], v[114:117], 0
	v_add_f32_e32 v64, v213, v176
	v_add_f32_e32 v64, v174, v64
	v_add_f32_e32 v64, v177, v64
	v_add_f32_e32 v64, v173, v64
	v_add_f32_e32 v64, v175, v64
	v_add_f32_e32 v64, v171, v64
	v_add_f32_e32 v64, v172, v64
	v_mfma_f32_32x32x16_bf16 v[80:95], v[84:87], v[114:117], 0
	ds_read_b128 v[208:211], v200 offset:49152
	ds_read_b128 v[214:217], v200 offset:57344
	v_add_f32_e32 v64, v167, v64
	v_add_f32_e32 v64, v169, v64
	v_add_f32_e32 v64, v166, v64
	v_add_f32_e32 v64, v168, v64
	v_add_f32_e32 v64, v163, v64
	v_add_f32_e32 v64, v165, v64
	v_add_f32_e32 v64, v162, v64
	s_waitcnt lgkmcnt(0)
	v_mfma_f32_32x32x16_bf16 v[96:111], v[208:211], v[122:125], v[96:111]
	v_exp_f32_e32 v212, v67
	v_add_f32_e32 v64, v164, v64
	v_add_f32_e32 v64, v170, v64
	v_exp_f32_e32 v218, v72
	v_exp_f32_e32 v219, v73
	v_exp_f32_e32 v220, v74
	v_exp_f32_e32 v221, v75
	v_mfma_f32_32x32x16_bf16 v[80:95], v[214:217], v[122:125], v[80:95]
	ds_read_b128 v[208:211], v202 offset:49152
	ds_read_b128 v[214:217], v202 offset:57344
	v_exp_f32_e32 v222, v76
	v_exp_f32_e32 v223, v77
	v_exp_f32_e32 v224, v78
	v_exp_f32_e32 v79, v79
	s_waitcnt lgkmcnt(0)
	v_mfma_f32_32x32x16_bf16 v[96:111], v[208:211], v[142:145], v[96:111]
	v_mfma_f32_32x32x16_bf16 v[80:95], v[214:217], v[142:145], v[80:95]
	ds_read_b128 v[208:211], v201 offset:49152
	ds_read_b128 v[214:217], v201 offset:57344
	s_waitcnt lgkmcnt(0)
	v_mfma_f32_32x32x16_bf16 v[96:111], v[208:211], v[138:141], v[96:111]
	v_mfma_f32_32x32x16_bf16 v[80:95], v[214:217], v[138:141], v[80:95]
	ds_read_b128 v[208:211], v203 offset:49152
	ds_read_b128 v[214:217], v203 offset:57344
	s_waitcnt lgkmcnt(0)
	v_mfma_f32_32x32x16_bf16 v[96:111], v[208:211], v[134:137], v[96:111]
	v_mfma_f32_32x32x16_bf16 v[80:95], v[214:217], v[134:137], v[80:95]
	ds_read_b128 v[208:211], v204 offset:49152
	ds_read_b128 v[214:217], v204 offset:57344
	s_waitcnt lgkmcnt(0)
	v_mfma_f32_32x32x16_bf16 v[96:111], v[208:211], v[130:133], v[96:111]
	v_mfma_f32_32x32x16_bf16 v[80:95], v[214:217], v[130:133], v[80:95]
	ds_read_b128 v[208:211], v206 offset:49152
	ds_read_b128 v[214:217], v206 offset:57344
	s_waitcnt lgkmcnt(0)
	v_mfma_f32_32x32x16_bf16 v[96:111], v[208:211], v[126:129], v[96:111]
	v_mfma_f32_32x32x16_bf16 v[80:95], v[214:217], v[126:129], v[80:95]
	ds_read_b128 v[208:211], v205 offset:49152
	ds_read_b128 v[214:217], v205 offset:57344
	s_waitcnt lgkmcnt(0)
	v_mfma_f32_32x32x16_bf16 v[96:111], v[208:211], v[118:121], v[96:111]
	v_exp_f32_e32 v210, v65
	v_exp_f32_e32 v211, v66
	v_add_f32_e32 v64, v210, v64
	v_add_f32_e32 v64, v211, v64
	v_add_f32_e32 v64, v212, v64
	v_mfma_f32_32x32x16_bf16 v[80:95], v[214:217], v[118:121], v[80:95]
	v_exp_f32_e32 v214, v68
	v_exp_f32_e32 v215, v69
	v_exp_f32_e32 v216, v70
	v_exp_f32_e32 v217, v71
	v_add_f32_e32 v64, v214, v64
	v_add_f32_e32 v64, v215, v64
	v_add_f32_e32 v64, v216, v64
	v_add_f32_e32 v64, v217, v64
	v_add_f32_e32 v64, v218, v64
	v_add_f32_e32 v64, v219, v64
	v_add_f32_e32 v64, v220, v64
	v_add_f32_e32 v64, v221, v64
	v_add_f32_e32 v64, v222, v64
	v_add_f32_e32 v64, v223, v64
	v_add_f32_e32 v64, v224, v64
	v_add_f32_e32 v208, v79, v64
	v_mov_b32_e32 v209, v208
	v_cvt_pk_bf16_f32 v64, v176, v213
	v_cvt_pk_bf16_f32 v65, v174, v177
	v_cvt_pk_bf16_f32 v66, v173, v175
	v_cvt_pk_bf16_f32 v67, v171, v172
	v_cvt_pk_bf16_f32 v68, v167, v169
	v_cvt_pk_bf16_f32 v69, v166, v168
	v_cvt_pk_bf16_f32 v70, v163, v165
	v_cvt_pk_bf16_f32 v71, v162, v164
	v_cvt_pk_bf16_f32 v72, v170, v210
	v_cvt_pk_bf16_f32 v73, v211, v212
	v_cvt_pk_bf16_f32 v74, v214, v215
	v_cvt_pk_bf16_f32 v75, v216, v217
	v_cvt_pk_bf16_f32 v76, v218, v219
	v_cvt_pk_bf16_f32 v77, v220, v221
	v_cvt_pk_bf16_f32 v78, v222, v223
	v_cvt_pk_bf16_f32 v79, v224, v79
	v_permlane32_swap_b32_e32 v208, v209
	v_permlane32_swap_b32_e32 v64, v66
	v_permlane32_swap_b32_e32 v65, v67
	v_permlane32_swap_b32_e32 v68, v70
	v_permlane32_swap_b32_e32 v69, v71
	v_permlane32_swap_b32_e32 v72, v74
	v_permlane32_swap_b32_e32 v73, v75
	v_permlane32_swap_b32_e32 v76, v78
	v_permlane32_swap_b32_e32 v77, v79
	s_mov_b32 s4, 0xfffb8000
	v_add_co_u32_e32 v166, vcc, s4, v188
	s_mov_b32 s4, 0xfffd0000
	s_nop 0
	v_addc_co_u32_e32 v167, vcc, -1, v189, vcc
	v_add_co_u32_e32 v174, vcc, s4, v188
	s_nop 1
	v_addc_co_u32_e32 v175, vcc, -1, v189, vcc
	global_load_dwordx4 v[162:165], v[166:167], off
	global_load_dwordx4 v[170:173], v[166:167], off offset:-512
	global_load_dwordx4 v[166:169], v[174:175], off
	global_load_dwordx4 v[174:177], v[174:175], off offset:-512
	v_cmp_neq_f32_e32 vcc, 0, v193
	ds_read_b64_tr_b16 v[210:211], v194 offset:0
	ds_read_b64_tr_b16 v[212:213], v194 offset:0x800
	ds_read_b64_tr_b16 v[214:215], v194 offset:0x1000
	ds_read_b64_tr_b16 v[216:217], v194 offset:0x1800
	s_cbranch_vccnz .LBB0_163
; #define SBAR() __builtin_amdgcn_sched_barrier(0)
; __device__ __forceinline__ void partialSM_pre(f32x16& p0, f32x16& p1, float& m_ref, float& alpha, const float thr2) {
;     ...
;   float pmax = p0[0];
; #pragma unroll
;   for (int r = 1; r < 16; ++r) pmax = fmaxf(pmax, p0[r]);
; #pragma unroll
;   for (int r = 0; r < 16; ++r) pmax = fmaxf(pmax, p1[r]);
;   { auto rr = __builtin_amdgcn_permlane32_swap(__float_as_uint(pmax), __float_as_uint(pmax), false, false);
;     pmax = fmaxf(__uint_as_float(rr[0]), __uint_as_float(rr[1])); }
;   if (__builtin_expect(__all(pmax <= thr2), 1)) { alpha = 1.f; }
; template <int OFF> __device__ __forceinline__ s16x4 tr_read(int vb) {
;   s16x4 r; asm volatile("ds_read_b64_tr_b16 %0, %1 offset:%2" : "=&v"(r) : "v"(vb), "i"(OFF) : "memory"); return r;
; }
; template <int D0> __device__ __forceinline__ void pv_one(f32x16& od, int vb, bf16x8 pa0, bf16x8 pa1, bf16x8 pa2, bf16x8 pa3) {
;   const s16x4 l0 = tr_read<v_rd_off(D0, 0, 0)>(vb), h0 = tr_read<v_rd_off(D0, 0, 1)>(vb), l1 = tr_read<v_rd_off(D0, 1, 0)>(vb), h1 = tr_read<v_rd_off(D0, 1, 1)>(vb);
;   const s16x4 l2 = tr_read<v_rd_off(D0, 2, 0)>(vb), h2 = tr_read<v_rd_off(D0, 2, 1)>(vb), l3 = tr_read<v_rd_off(D0, 3, 0)>(vb), h3 = tr_read<v_rd_off(D0, 3, 1)>(vb);
;   asm volatile("s_waitcnt lgkmcnt(0)" ::: "memory"); SBAR();
;     ...
;   od = __builtin_amdgcn_mfma_f32_32x32x16_bf16(pa0, PK(l0, h0), od, 0, 0, 0);
;   od = __builtin_amdgcn_mfma_f32_32x32x16_bf16(pa1, PK(l1, h1), od, 0, 0, 0);
;   od = __builtin_amdgcn_mfma_f32_32x32x16_bf16(pa2, PK(l2, h2), od, 0, 0, 0);
;   od = __builtin_amdgcn_mfma_f32_32x32x16_bf16(pa3, PK(l3, h3), od, 0, 0, 0);
;     ...
; }
; __device__ __forceinline__ void pv_d0(f32x16* o, int vb, bf16x8 pa0, bf16x8 pa1, bf16x8 pa2, bf16x8 pa3) {
;   pv_one<0>(o[0], vb, pa0, pa1, pa2, pa3); pv_one<1>(o[1], vb, pa0, pa1, pa2, pa3); pv_one<2>(o[2], vb, pa0, pa1, pa2, pa3); pv_one<3>(o[3], vb, pa0, pa1, pa2, pa3);
.LBB0_147:
	v_max_f32_e32 v180, v96, v97
	v_max3_f32 v180, v180, v98, v99
	v_max3_f32 v180, v180, v100, v101
	v_max3_f32 v180, v180, v102, v103
	v_max3_f32 v180, v180, v104, v105
	v_max3_f32 v180, v180, v106, v107
	v_max3_f32 v180, v180, v108, v109
	v_max3_f32 v180, v180, v110, v111
	v_max3_f32 v180, v180, v80, v81
	v_max3_f32 v180, v180, v82, v83
	v_max3_f32 v180, v180, v84, v85
	v_max3_f32 v180, v180, v86, v87
	v_max3_f32 v180, v180, v88, v89
	v_max3_f32 v180, v180, v90, v91
	v_max3_f32 v180, v180, v92, v93
	v_max3_f32 v180, v180, v94, v95
	v_mov_b32_e32 v182, v180
	s_nop 1
	v_permlane32_swap_b32_e32 v180, v182
	v_max_f32_e32 v180, v180, v182
	ds_read_b64_tr_b16 v[218:219], v194 offset:0x2000
	ds_read_b64_tr_b16 v[220:221], v194 offset:0x2800
	ds_read_b64_tr_b16 v[222:223], v194 offset:0x3000
	ds_read_b64_tr_b16 v[224:225], v194 offset:0x3800
	s_waitcnt lgkmcnt(4)
	v_mfma_f32_32x32x16_bf16 v[0:15], v[64:67], v[210:213], v[0:15]
	ds_read_b64_tr_b16 v[210:211], v194 offset:0x200
	ds_read_b64_tr_b16 v[212:213], v194 offset:0xa00
	v_mfma_f32_32x32x16_bf16 v[0:15], v[68:71], v[214:217], v[0:15]
	ds_read_b64_tr_b16 v[214:215], v194 offset:0x1200
	ds_read_b64_tr_b16 v[216:217], v194 offset:0x1a00
	s_waitcnt lgkmcnt(4)
	v_mfma_f32_32x32x16_bf16 v[0:15], v[72:75], v[218:221], v[0:15]
	ds_read_b64_tr_b16 v[218:219], v194 offset:0x2200
	ds_read_b64_tr_b16 v[220:221], v194 offset:0x2a00
	v_mfma_f32_32x32x16_bf16 v[0:15], v[76:79], v[222:225], v[0:15]
	ds_read_b64_tr_b16 v[222:223], v194 offset:0x3200
	ds_read_b64_tr_b16 v[224:225], v194 offset:0x3a00
	s_waitcnt lgkmcnt(4)
	v_mfma_f32_32x32x16_bf16 v[48:63], v[64:67], v[210:213], v[48:63]
	ds_read_b64_tr_b16 v[210:211], v194 offset:0x400
	ds_read_b64_tr_b16 v[212:213], v194 offset:0xc00
	v_mfma_f32_32x32x16_bf16 v[48:63], v[68:71], v[214:217], v[48:63]
	ds_read_b64_tr_b16 v[214:215], v194 offset:0x1400
	ds_read_b64_tr_b16 v[216:217], v194 offset:0x1c00
	s_waitcnt lgkmcnt(4)
	v_mfma_f32_32x32x16_bf16 v[48:63], v[72:75], v[218:221], v[48:63]
	ds_read_b64_tr_b16 v[218:219], v194 offset:0x2400
	ds_read_b64_tr_b16 v[220:221], v194 offset:0x2c00
	v_mfma_f32_32x32x16_bf16 v[48:63], v[76:79], v[222:225], v[48:63]
	ds_read_b64_tr_b16 v[222:223], v194 offset:0x3400
	ds_read_b64_tr_b16 v[224:225], v194 offset:0x3c00
	s_waitcnt lgkmcnt(4)
	v_mfma_f32_32x32x16_bf16 v[32:47], v[64:67], v[210:213], v[32:47]
	ds_read_b64_tr_b16 v[210:211], v194 offset:0x600
	ds_read_b64_tr_b16 v[212:213], v194 offset:0xe00
	v_mfma_f32_32x32x16_bf16 v[32:47], v[68:71], v[214:217], v[32:47]
	ds_read_b64_tr_b16 v[214:215], v194 offset:0x1600
	ds_read_b64_tr_b16 v[216:217], v194 offset:0x1e00
	s_waitcnt lgkmcnt(4)
	v_mfma_f32_32x32x16_bf16 v[32:47], v[72:75], v[218:221], v[32:47]
	ds_read_b64_tr_b16 v[218:219], v194 offset:0x2600
	ds_read_b64_tr_b16 v[220:221], v194 offset:0x2e00
	v_mfma_f32_32x32x16_bf16 v[32:47], v[76:79], v[222:225], v[32:47]
	ds_read_b64_tr_b16 v[222:223], v194 offset:0x3600
	ds_read_b64_tr_b16 v[224:225], v194 offset:0x3e00
	s_waitcnt lgkmcnt(4)
	v_mfma_f32_32x32x16_bf16 v[16:31], v[64:67], v[210:213], v[16:31]
	v_mfma_f32_32x32x16_bf16 v[16:31], v[68:71], v[214:217], v[16:31]
	s_waitcnt lgkmcnt(0)
	v_mfma_f32_32x32x16_bf16 v[16:31], v[72:75], v[218:221], v[16:31]
	s_waitcnt vmcnt(4)
	ds_write_b128 v195, v[150:153] offset:32768
	ds_write_b128 v196, v[146:149] offset:32768
	v_mfma_f32_32x32x16_bf16 v[16:31], v[76:79], v[222:225], v[16:31]
	v_cmp_ge_f32_e32 vcc, s45, v180
	s_cmp_eq_u64 vcc, exec
	v_mov_b32_e32 v210, 1.0
	s_cbranch_scc0 .LBB0_164

; #define SBAR() __builtin_amdgcn_sched_barrier(0)
; __device__ __forceinline__ void partialSM_pre(f32x16& p0, f32x16& p1, float& m_ref, float& alpha, const float thr2) {
;     ...
;   float pmax = p0[0];
; #pragma unroll
;   for (int r = 1; r < 16; ++r) pmax = fmaxf(pmax, p0[r]);
; #pragma unroll
;   for (int r = 0; r < 16; ++r) pmax = fmaxf(pmax, p1[r]);
;   { auto rr = __builtin_amdgcn_permlane32_swap(__float_as_uint(pmax), __float_as_uint(pmax), false, false);
;     pmax = fmaxf(__uint_as_float(rr[0]), __uint_as_float(rr[1])); }
;   if (__builtin_expect(__all(pmax <= thr2), 1)) { alpha = 1.f; }
; template <int OFF> __device__ __forceinline__ s16x4 tr_read(int vb) {
;   s16x4 r; asm volatile("ds_read_b64_tr_b16 %0, %1 offset:%2" : "=&v"(r) : "v"(vb), "i"(OFF) : "memory"); return r;
; }
; template <int D0> __device__ __forceinline__ void pv_one(f32x16& od, int vb, bf16x8 pa0, bf16x8 pa1, bf16x8 pa2, bf16x8 pa3) {
;   const s16x4 l0 = tr_read<v_rd_off(D0, 0, 0)>(vb), h0 = tr_read<v_rd_off(D0, 0, 1)>(vb), l1 = tr_read<v_rd_off(D0, 1, 0)>(vb), h1 = tr_read<v_rd_off(D0, 1, 1)>(vb);
;   const s16x4 l2 = tr_read<v_rd_off(D0, 2, 0)>(vb), h2 = tr_read<v_rd_off(D0, 2, 1)>(vb), l3 = tr_read<v_rd_off(D0, 3, 0)>(vb), h3 = tr_read<v_rd_off(D0, 3, 1)>(vb);
;   asm volatile("s_waitcnt lgkmcnt(0)" ::: "memory"); SBAR();
;     ...
;   od = __builtin_amdgcn_mfma_f32_32x32x16_bf16(pa0, PK(l0, h0), od, 0, 0, 0);
;   od = __builtin_amdgcn_mfma_f32_32x32x16_bf16(pa1, PK(l1, h1), od, 0, 0, 0);
;   od = __builtin_amdgcn_mfma_f32_32x32x16_bf16(pa2, PK(l2, h2), od, 0, 0, 0);
;   od = __builtin_amdgcn_mfma_f32_32x32x16_bf16(pa3, PK(l3, h3), od, 0, 0, 0);
;     ...
; }
; __device__ __forceinline__ void pv_d0(f32x16* o, int vb, bf16x8 pa0, bf16x8 pa1, bf16x8 pa2, bf16x8 pa3) {
;   pv_one<0>(o[0], vb, pa0, pa1, pa2, pa3); pv_one<1>(o[1], vb, pa0, pa1, pa2, pa3); pv_one<2>(o[2], vb, pa0, pa1, pa2, pa3); pv_one<3>(o[3], vb, pa0, pa1, pa2, pa3);
.LBB0_155:
	v_cmp_neq_f32_e32 vcc, 0, v193
	ds_read_b64_tr_b16 v[214:215], v191 offset:0
	ds_read_b64_tr_b16 v[216:217], v191 offset:0x800
	ds_read_b64_tr_b16 v[218:219], v191 offset:0x1000
	ds_read_b64_tr_b16 v[220:221], v191 offset:0x1800
	s_cbranch_vccnz .LBB0_165
.LBB0_156:
	v_max_f32_e32 v180, v96, v97
	v_max3_f32 v180, v180, v98, v99
	v_max3_f32 v180, v180, v100, v101
	v_max3_f32 v180, v180, v102, v103
	v_max3_f32 v180, v180, v104, v105
	v_max3_f32 v180, v180, v106, v107
	v_max3_f32 v180, v180, v108, v109
	v_max3_f32 v180, v180, v110, v111
	v_max3_f32 v180, v180, v64, v65
	v_max3_f32 v180, v180, v66, v67
	v_max3_f32 v180, v180, v68, v69
	v_max3_f32 v180, v180, v70, v71
	v_max3_f32 v180, v180, v72, v73
	v_max3_f32 v180, v180, v74, v75
	v_max3_f32 v180, v180, v76, v77
	v_max3_f32 v180, v180, v78, v79
	v_mov_b32_e32 v182, v180
	s_nop 1
	v_permlane32_swap_b32_e32 v180, v182
	v_max_f32_e32 v180, v180, v182
	ds_read_b64_tr_b16 v[222:223], v191 offset:0x2000
	ds_read_b64_tr_b16 v[224:225], v191 offset:0x2800
	ds_read_b64_tr_b16 v[234:235], v191 offset:0x3000
	ds_read_b64_tr_b16 v[236:237], v191 offset:0x3800
	s_waitcnt lgkmcnt(4)
	v_mfma_f32_32x32x16_bf16 v[0:15], v[80:83], v[214:217], v[0:15]
	ds_read_b64_tr_b16 v[214:215], v191 offset:0x200
	ds_read_b64_tr_b16 v[216:217], v191 offset:0xa00
	v_mfma_f32_32x32x16_bf16 v[0:15], v[84:87], v[218:221], v[0:15]
	ds_read_b64_tr_b16 v[218:219], v191 offset:0x1200
	ds_read_b64_tr_b16 v[220:221], v191 offset:0x1a00
	s_waitcnt lgkmcnt(4)
	v_mfma_f32_32x32x16_bf16 v[0:15], v[88:91], v[222:225], v[0:15]
	ds_read_b64_tr_b16 v[222:223], v191 offset:0x2200
	ds_read_b64_tr_b16 v[224:225], v191 offset:0x2a00
	v_mfma_f32_32x32x16_bf16 v[0:15], v[92:95], v[234:237], v[0:15]
	ds_read_b64_tr_b16 v[234:235], v191 offset:0x3200
	ds_read_b64_tr_b16 v[236:237], v191 offset:0x3a00
	s_waitcnt lgkmcnt(4)
	v_mfma_f32_32x32x16_bf16 v[48:63], v[80:83], v[214:217], v[48:63]
	ds_read_b64_tr_b16 v[214:215], v191 offset:0x400
	ds_read_b64_tr_b16 v[216:217], v191 offset:0xc00
	v_mfma_f32_32x32x16_bf16 v[48:63], v[84:87], v[218:221], v[48:63]
	ds_read_b64_tr_b16 v[218:219], v191 offset:0x1400
	ds_read_b64_tr_b16 v[220:221], v191 offset:0x1c00
	s_waitcnt lgkmcnt(4)
	v_mfma_f32_32x32x16_bf16 v[48:63], v[88:91], v[222:225], v[48:63]
	ds_read_b64_tr_b16 v[222:223], v191 offset:0x2400
	ds_read_b64_tr_b16 v[224:225], v191 offset:0x2c00
	v_mfma_f32_32x32x16_bf16 v[48:63], v[92:95], v[234:237], v[48:63]
	ds_read_b64_tr_b16 v[234:235], v191 offset:0x3400
	ds_read_b64_tr_b16 v[236:237], v191 offset:0x3c00
	s_waitcnt lgkmcnt(4)
	v_mfma_f32_32x32x16_bf16 v[32:47], v[80:83], v[214:217], v[32:47]
	ds_read_b64_tr_b16 v[214:215], v191 offset:0x600
	ds_read_b64_tr_b16 v[216:217], v191 offset:0xe00
	v_mfma_f32_32x32x16_bf16 v[32:47], v[84:87], v[218:221], v[32:47]
	ds_read_b64_tr_b16 v[218:219], v191 offset:0x1600
	ds_read_b64_tr_b16 v[220:221], v191 offset:0x1e00
	s_waitcnt lgkmcnt(4)
	v_mfma_f32_32x32x16_bf16 v[32:47], v[88:91], v[222:225], v[32:47]
	ds_read_b64_tr_b16 v[222:223], v191 offset:0x2600
	ds_read_b64_tr_b16 v[224:225], v191 offset:0x2e00
	v_mfma_f32_32x32x16_bf16 v[32:47], v[92:95], v[234:237], v[32:47]
	ds_read_b64_tr_b16 v[234:235], v191 offset:0x3600
	ds_read_b64_tr_b16 v[236:237], v191 offset:0x3e00
	s_waitcnt lgkmcnt(4)
	v_mfma_f32_32x32x16_bf16 v[16:31], v[80:83], v[214:217], v[16:31]
	v_mfma_f32_32x32x16_bf16 v[16:31], v[84:87], v[218:221], v[16:31]
	s_waitcnt lgkmcnt(0)
	v_mfma_f32_32x32x16_bf16 v[16:31], v[88:91], v[222:225], v[16:31]
	s_waitcnt vmcnt(4)
	ds_write_b128 v195, v[170:173] offset:49152
	ds_write_b128 v196, v[174:177] offset:49152
	v_mfma_f32_32x32x16_bf16 v[16:31], v[92:95], v[234:237], v[16:31]
	v_cmp_ge_f32_e32 vcc, s45, v180
	s_cmp_eq_u64 vcc, exec
	v_mov_b32_e32 v170, 1.0
	s_cbranch_scc0 .LBB0_166

; #define SBAR() __builtin_amdgcn_sched_barrier(0)
; #define KWRITE(b, src0, src1) do { if constexpr (ND0 == 4) { *(bf16x8*)(K_lds + (b) * SHM_K + KSWZ(kr, kcb)) = src0; } \
;     else { int kc = sc * 2; *(bf16x8*)(K_lds + (b) * SHM_K + KSWZ(sr, kc)) = src0; *(bf16x8*)(K_lds + (b) * SHM_K + KSWZ(32 + sr, kc)) = src1; } } while (0)
; #define SLOAD_B(k0) do { vs0b = *reinterpret_cast<const bf16x8*>(&Vh[(long)((k0) + sr) * LDK + sc]); vs1b = *reinterpret_cast<const bf16x8*>(&Vh[(long)((k0) + 32 + sr) * LDK + sc]); KLOAD(ks0b, ks1b, k0); } while (0)
; #define PSM(P0, P1, MN, AL) do { if constexpr (PRE) partialSM_pre(P0, P1, m_reg, AL, 11.541560327111707f); else partialSM(P0, P1, m_reg, MN, AL, C, thr_raw); } while (0)
; __device__ __forceinline__ void finishSM(f32x16& p0, f32x16& p1, float alpha, float& l_reg, bf16x8& pa0, bf16x8& pa1, bf16x8& pa2, bf16x8& pa3) {
; #pragma unroll
;   for (int r = 0; r < 16; ++r) p1[r] = __builtin_amdgcn_exp2f(p1[r]);
;   float ps = 0;
; #pragma unroll
;   for (int r = 0; r < 16; ++r) ps += p0[r];
; #pragma unroll
;   for (int r = 0; r < 16; ++r) ps += p1[r];
;   { auto rr = __builtin_amdgcn_permlane32_swap(__float_as_uint(ps), __float_as_uint(ps), false, false);
;     ps = __uint_as_float(rr[0]) + __uint_as_float(rr[1]); }
;   l_reg = l_reg * alpha + ps;
;     ...
;   PK4(p0, 0, pa0); PK4(p0, 8, pa1); PK4(p1, 0, pa2); PK4(p1, 8, pa3);
;     ...
; }
; template <int ND0>
; __device__ __forceinline__ void qkt(f32x16& p0, f32x16& p1, const char* Ks, const bf16x8* qr, int r32, int hi) {
;   p0 = f32x16{}; p1 = f32x16{};
; #pragma unroll
;   for (int d0 = 0; d0 < ND0; ++d0) { int cb = (d0 * 16 + hi * 8) * 2;
;     bf16x8 b0 = *reinterpret_cast<const bf16x8*>(Ks + KSWZ(r32, cb));
;     bf16x8 b1 = *reinterpret_cast<const bf16x8*>(Ks + KSWZ(32 + r32, cb));
;     p0 = __builtin_amdgcn_mfma_f32_32x32x16_bf16(b0, qr[d0], p0, 0, 0, 0);
;     p1 = __builtin_amdgcn_mfma_f32_32x32x16_bf16(b1, qr[d0], p1, 0, 0, 0); }
; }
; template <int ND0, int LDQ, int LDK, int LDO> ...
;     ...
;     SBAR(); qkt<ND0>(pB0, pB1, Kq1, qr, r32, hi);
;     finishSM(pA0, pA1, alA, l_reg, pa0, pa1, pa2, pa3); SBAR();
;     SLOAD_B((j + 2) * KVBLK); SBAR();
;     pv_d0(o, vb0, pa0, pa1, pa2, pa3); KWRITE(0, ks0a, ks1a); PSM(pB0, pB1, mnB, alB);
.LBB0_214:
	v_exp_f32_e32 v150, v64
	s_waitcnt lgkmcnt(0)
	v_mfma_f32_32x32x16_bf16 v[96:111], v[80:83], v[126:129], 0
	v_add_f32_e32 v64, v206, v176
	v_add_f32_e32 v64, v174, v64
	v_add_f32_e32 v64, v177, v64
	v_add_f32_e32 v64, v152, v64
	v_add_f32_e32 v64, v175, v64
	v_add_f32_e32 v64, v151, v64
	v_add_f32_e32 v64, v153, v64
	v_mfma_f32_32x32x16_bf16 v[80:95], v[84:87], v[126:129], 0
	ds_read_b128 v[202:205], v198 offset:49152
	ds_read_b128 v[208:211], v198 offset:57344
	v_add_f32_e32 v64, v147, v64
	v_add_f32_e32 v64, v149, v64
	v_add_f32_e32 v64, v145, v64
	v_add_f32_e32 v64, v148, v64
	v_add_f32_e32 v64, v143, v64
	v_add_f32_e32 v64, v146, v64
	v_add_f32_e32 v64, v142, v64
	s_waitcnt lgkmcnt(0)
	v_mfma_f32_32x32x16_bf16 v[96:111], v[202:205], v[122:125], v[96:111]
	v_add_f32_e32 v64, v144, v64
	v_exp_f32_e32 v207, v68
	v_add_f32_e32 v64, v150, v64
	v_exp_f32_e32 v212, v73
	v_exp_f32_e32 v213, v74
	v_exp_f32_e32 v214, v75
	v_exp_f32_e32 v215, v76
	v_mfma_f32_32x32x16_bf16 v[80:95], v[208:211], v[122:125], v[80:95]
	ds_read_b128 v[222:225], v199 offset:49152
	ds_read_b128 v[234:237], v199 offset:57344
	v_exp_f32_e32 v216, v77
	v_exp_f32_e32 v217, v78
	v_exp_f32_e32 v79, v79
	s_waitcnt lgkmcnt(0)
	v_mfma_f32_32x32x16_bf16 v[96:111], v[222:225], v[118:121], v[96:111]
	v_mfma_f32_32x32x16_bf16 v[80:95], v[234:237], v[118:121], v[80:95]
	ds_read_b128 v[238:241], v196 offset:49152
	ds_read_b128 v[244:247], v196 offset:57344
	s_waitcnt lgkmcnt(0)
	v_mfma_f32_32x32x16_bf16 v[96:111], v[238:241], v[114:117], v[96:111]
	v_exp_f32_e32 v203, v65
	v_exp_f32_e32 v204, v66
	v_exp_f32_e32 v205, v67
	v_add_f32_e32 v64, v203, v64
	v_add_f32_e32 v64, v204, v64
	v_add_f32_e32 v64, v205, v64
	v_mfma_f32_32x32x16_bf16 v[80:95], v[244:247], v[114:117], v[80:95]
	v_exp_f32_e32 v208, v69
	v_exp_f32_e32 v209, v70
	v_exp_f32_e32 v210, v71
	v_exp_f32_e32 v211, v72
	v_add_f32_e32 v64, v207, v64
	v_add_f32_e32 v64, v208, v64
	v_add_f32_e32 v64, v209, v64
	v_add_f32_e32 v64, v210, v64
	v_add_f32_e32 v64, v211, v64
	v_add_f32_e32 v64, v212, v64
	v_add_f32_e32 v64, v213, v64
	v_add_f32_e32 v64, v214, v64
	v_add_f32_e32 v64, v215, v64
	v_add_f32_e32 v64, v216, v64
	v_add_f32_e32 v64, v217, v64
	v_add_f32_e32 v201, v79, v64
	v_mov_b32_e32 v202, v201
	v_cvt_pk_bf16_f32 v64, v176, v206
	v_cvt_pk_bf16_f32 v65, v174, v177
	v_cvt_pk_bf16_f32 v66, v152, v175
	v_cvt_pk_bf16_f32 v67, v151, v153
	v_cvt_pk_bf16_f32 v68, v147, v149
	v_cvt_pk_bf16_f32 v69, v145, v148
	v_cvt_pk_bf16_f32 v70, v143, v146
	v_cvt_pk_bf16_f32 v71, v142, v144
	v_cvt_pk_bf16_f32 v72, v150, v203
	v_cvt_pk_bf16_f32 v73, v204, v205
	v_cvt_pk_bf16_f32 v74, v207, v208
	v_cvt_pk_bf16_f32 v75, v209, v210
	v_cvt_pk_bf16_f32 v76, v211, v212
	v_cvt_pk_bf16_f32 v77, v213, v214
	v_cvt_pk_bf16_f32 v78, v215, v216
	v_cvt_pk_bf16_f32 v79, v217, v79
	v_permlane32_swap_b32_e32 v201, v202
	v_permlane32_swap_b32_e32 v64, v66
	v_permlane32_swap_b32_e32 v65, v67
	v_permlane32_swap_b32_e32 v68, v70
	v_permlane32_swap_b32_e32 v69, v71
	v_permlane32_swap_b32_e32 v72, v74
	v_permlane32_swap_b32_e32 v73, v75
	v_permlane32_swap_b32_e32 v76, v78
	v_permlane32_swap_b32_e32 v77, v79
	global_load_dwordx4 v[142:145], v[172:173], off
	v_lshl_add_u64 v[174:175], v[172:173], 0, s[34:35]
	global_load_dwordx4 v[146:149], v[174:175], off
	global_load_dwordx4 v[150:153], v[170:171], off offset:2048
	v_lshl_add_u64 v[172:173], v[172:173], 0, s[46:47]
	v_lshl_add_u64 v[170:171], v[170:171], 0, s[46:47]
	v_cmp_neq_f32_e32 vcc, 0, v191
	ds_read_b64_tr_b16 v[204:205], v192 offset:0
	ds_read_b64_tr_b16 v[206:207], v192 offset:0x800
	ds_read_b64_tr_b16 v[208:209], v192 offset:0x1000
	ds_read_b64_tr_b16 v[210:211], v192 offset:0x1800
	s_cbranch_vccnz .LBB0_230
; #define SBAR() __builtin_amdgcn_sched_barrier(0)
; __device__ __forceinline__ void partialSM_pre(f32x16& p0, f32x16& p1, float& m_ref, float& alpha, const float thr2) {
;     ...
;   float pmax = p0[0];
; #pragma unroll
;   for (int r = 1; r < 16; ++r) pmax = fmaxf(pmax, p0[r]);
; #pragma unroll
;   for (int r = 0; r < 16; ++r) pmax = fmaxf(pmax, p1[r]);
;   { auto rr = __builtin_amdgcn_permlane32_swap(__float_as_uint(pmax), __float_as_uint(pmax), false, false);
;     pmax = fmaxf(__uint_as_float(rr[0]), __uint_as_float(rr[1])); }
;   if (__builtin_expect(__all(pmax <= thr2), 1)) { alpha = 1.f; }
; template <int OFF> __device__ __forceinline__ s16x4 tr_read(int vb) {
;   s16x4 r; asm volatile("ds_read_b64_tr_b16 %0, %1 offset:%2" : "=&v"(r) : "v"(vb), "i"(OFF) : "memory"); return r;
; }
; template <int D0> __device__ __forceinline__ void pv_one(f32x16& od, int vb, bf16x8 pa0, bf16x8 pa1, bf16x8 pa2, bf16x8 pa3) {
;   const s16x4 l0 = tr_read<v_rd_off(D0, 0, 0)>(vb), h0 = tr_read<v_rd_off(D0, 0, 1)>(vb), l1 = tr_read<v_rd_off(D0, 1, 0)>(vb), h1 = tr_read<v_rd_off(D0, 1, 1)>(vb);
;   const s16x4 l2 = tr_read<v_rd_off(D0, 2, 0)>(vb), h2 = tr_read<v_rd_off(D0, 2, 1)>(vb), l3 = tr_read<v_rd_off(D0, 3, 0)>(vb), h3 = tr_read<v_rd_off(D0, 3, 1)>(vb);
;   asm volatile("s_waitcnt lgkmcnt(0)" ::: "memory"); SBAR();
;     ...
;   od = __builtin_amdgcn_mfma_f32_32x32x16_bf16(pa0, PK(l0, h0), od, 0, 0, 0);
;   od = __builtin_amdgcn_mfma_f32_32x32x16_bf16(pa1, PK(l1, h1), od, 0, 0, 0);
;   od = __builtin_amdgcn_mfma_f32_32x32x16_bf16(pa2, PK(l2, h2), od, 0, 0, 0);
;   od = __builtin_amdgcn_mfma_f32_32x32x16_bf16(pa3, PK(l3, h3), od, 0, 0, 0);
;     ...
; }
; __device__ __forceinline__ void pv_d0(f32x16* o, int vb, bf16x8 pa0, bf16x8 pa1, bf16x8 pa2, bf16x8 pa3) {
;   pv_one<0>(o[0], vb, pa0, pa1, pa2, pa3); pv_one<1>(o[1], vb, pa0, pa1, pa2, pa3); pv_one<2>(o[2], vb, pa0, pa1, pa2, pa3); pv_one<3>(o[3], vb, pa0, pa1, pa2, pa3);
.LBB0_215:
	v_max_f32_e32 v252, v96, v97
	v_max3_f32 v252, v252, v98, v99
	v_max3_f32 v252, v252, v100, v101
	v_max3_f32 v252, v252, v102, v103
	v_max3_f32 v252, v252, v104, v105
	v_max3_f32 v252, v252, v106, v107
	v_max3_f32 v252, v252, v108, v109
	v_max3_f32 v252, v252, v110, v111
	v_max3_f32 v252, v252, v80, v81
	v_max3_f32 v252, v252, v82, v83
	v_max3_f32 v252, v252, v84, v85
	v_max3_f32 v252, v252, v86, v87
	v_max3_f32 v252, v252, v88, v89
	v_max3_f32 v252, v252, v90, v91
	v_max3_f32 v252, v252, v92, v93
	v_max3_f32 v252, v252, v94, v95
	v_mov_b32_e32 v253, v252
	s_nop 1
	v_permlane32_swap_b32_e32 v252, v253
	v_max_f32_e32 v252, v252, v253
	ds_read_b64_tr_b16 v[212:213], v192 offset:0x2000
	ds_read_b64_tr_b16 v[214:215], v192 offset:0x2800
	ds_read_b64_tr_b16 v[216:217], v192 offset:0x3000
	ds_read_b64_tr_b16 v[218:219], v192 offset:0x3800
	s_waitcnt lgkmcnt(4)
	v_mfma_f32_32x32x16_bf16 v[0:15], v[64:67], v[204:207], v[0:15]
	ds_read_b64_tr_b16 v[204:205], v192 offset:0x200
	ds_read_b64_tr_b16 v[206:207], v192 offset:0xa00
	v_mfma_f32_32x32x16_bf16 v[0:15], v[68:71], v[208:211], v[0:15]
	ds_read_b64_tr_b16 v[208:209], v192 offset:0x1200
	ds_read_b64_tr_b16 v[210:211], v192 offset:0x1a00
	s_waitcnt lgkmcnt(4)
	v_mfma_f32_32x32x16_bf16 v[0:15], v[72:75], v[212:215], v[0:15]
	ds_read_b64_tr_b16 v[212:213], v192 offset:0x2200
	ds_read_b64_tr_b16 v[214:215], v192 offset:0x2a00
	v_mfma_f32_32x32x16_bf16 v[0:15], v[76:79], v[216:219], v[0:15]
	ds_read_b64_tr_b16 v[216:217], v192 offset:0x3200
	ds_read_b64_tr_b16 v[218:219], v192 offset:0x3a00
	s_waitcnt lgkmcnt(4)
	v_mfma_f32_32x32x16_bf16 v[48:63], v[64:67], v[204:207], v[48:63]
	ds_read_b64_tr_b16 v[204:205], v192 offset:0x400
	ds_read_b64_tr_b16 v[206:207], v192 offset:0xc00
	v_mfma_f32_32x32x16_bf16 v[48:63], v[68:71], v[208:211], v[48:63]
	ds_read_b64_tr_b16 v[208:209], v192 offset:0x1400
	ds_read_b64_tr_b16 v[210:211], v192 offset:0x1c00
	s_waitcnt lgkmcnt(4)
	v_mfma_f32_32x32x16_bf16 v[48:63], v[72:75], v[212:215], v[48:63]
	ds_read_b64_tr_b16 v[212:213], v192 offset:0x2400
	ds_read_b64_tr_b16 v[214:215], v192 offset:0x2c00
	v_mfma_f32_32x32x16_bf16 v[48:63], v[76:79], v[216:219], v[48:63]
	ds_read_b64_tr_b16 v[216:217], v192 offset:0x3400
	ds_read_b64_tr_b16 v[218:219], v192 offset:0x3c00
	s_waitcnt lgkmcnt(4)
	v_mfma_f32_32x32x16_bf16 v[32:47], v[64:67], v[204:207], v[32:47]
	ds_read_b64_tr_b16 v[204:205], v192 offset:0x600
	ds_read_b64_tr_b16 v[206:207], v192 offset:0xe00
	v_mfma_f32_32x32x16_bf16 v[32:47], v[68:71], v[208:211], v[32:47]
	ds_read_b64_tr_b16 v[208:209], v192 offset:0x1600
	ds_read_b64_tr_b16 v[210:211], v192 offset:0x1e00
	s_waitcnt lgkmcnt(4)
	v_mfma_f32_32x32x16_bf16 v[32:47], v[72:75], v[212:215], v[32:47]
	ds_read_b64_tr_b16 v[212:213], v192 offset:0x2600
	ds_read_b64_tr_b16 v[214:215], v192 offset:0x2e00
	v_mfma_f32_32x32x16_bf16 v[32:47], v[76:79], v[216:219], v[32:47]
	ds_read_b64_tr_b16 v[216:217], v192 offset:0x3600
	ds_read_b64_tr_b16 v[218:219], v192 offset:0x3e00
	s_waitcnt lgkmcnt(4)
	v_mfma_f32_32x32x16_bf16 v[16:31], v[64:67], v[204:207], v[16:31]
	v_mfma_f32_32x32x16_bf16 v[16:31], v[68:71], v[208:211], v[16:31]
	s_waitcnt lgkmcnt(0)
	v_mfma_f32_32x32x16_bf16 v[16:31], v[72:75], v[212:215], v[16:31]
	s_waitcnt vmcnt(3)
	ds_write_b128 v195, v[138:141] offset:32768
	v_mfma_f32_32x32x16_bf16 v[16:31], v[76:79], v[216:219], v[16:31]
	v_cmp_ge_f32_e32 vcc, s45, v252
	s_cmp_eq_u64 vcc, exec
	v_mov_b32_e32 v203, 1.0
	s_cbranch_scc0 .LBB0_231

; #define SBAR() __builtin_amdgcn_sched_barrier(0)
; __device__ __forceinline__ void partialSM_pre(f32x16& p0, f32x16& p1, float& m_ref, float& alpha, const float thr2) {
;     ...
;   float pmax = p0[0];
; #pragma unroll
;   for (int r = 1; r < 16; ++r) pmax = fmaxf(pmax, p0[r]);
; #pragma unroll
;   for (int r = 0; r < 16; ++r) pmax = fmaxf(pmax, p1[r]);
;   { auto rr = __builtin_amdgcn_permlane32_swap(__float_as_uint(pmax), __float_as_uint(pmax), false, false);
;     pmax = fmaxf(__uint_as_float(rr[0]), __uint_as_float(rr[1])); }
;   if (__builtin_expect(__all(pmax <= thr2), 1)) { alpha = 1.f; }
; template <int OFF> __device__ __forceinline__ s16x4 tr_read(int vb) {
;   s16x4 r; asm volatile("ds_read_b64_tr_b16 %0, %1 offset:%2" : "=&v"(r) : "v"(vb), "i"(OFF) : "memory"); return r;
; }
; template <int D0> __device__ __forceinline__ void pv_one(f32x16& od, int vb, bf16x8 pa0, bf16x8 pa1, bf16x8 pa2, bf16x8 pa3) {
;   const s16x4 l0 = tr_read<v_rd_off(D0, 0, 0)>(vb), h0 = tr_read<v_rd_off(D0, 0, 1)>(vb), l1 = tr_read<v_rd_off(D0, 1, 0)>(vb), h1 = tr_read<v_rd_off(D0, 1, 1)>(vb);
;   const s16x4 l2 = tr_read<v_rd_off(D0, 2, 0)>(vb), h2 = tr_read<v_rd_off(D0, 2, 1)>(vb), l3 = tr_read<v_rd_off(D0, 3, 0)>(vb), h3 = tr_read<v_rd_off(D0, 3, 1)>(vb);
;   asm volatile("s_waitcnt lgkmcnt(0)" ::: "memory"); SBAR();
;     ...
;   od = __builtin_amdgcn_mfma_f32_32x32x16_bf16(pa0, PK(l0, h0), od, 0, 0, 0);
;   od = __builtin_amdgcn_mfma_f32_32x32x16_bf16(pa1, PK(l1, h1), od, 0, 0, 0);
;   od = __builtin_amdgcn_mfma_f32_32x32x16_bf16(pa2, PK(l2, h2), od, 0, 0, 0);
;   od = __builtin_amdgcn_mfma_f32_32x32x16_bf16(pa3, PK(l3, h3), od, 0, 0, 0);
;     ...
; }
; __device__ __forceinline__ void pv_d0(f32x16* o, int vb, bf16x8 pa0, bf16x8 pa1, bf16x8 pa2, bf16x8 pa3) {
;   pv_one<0>(o[0], vb, pa0, pa1, pa2, pa3); pv_one<1>(o[1], vb, pa0, pa1, pa2, pa3); pv_one<2>(o[2], vb, pa0, pa1, pa2, pa3); pv_one<3>(o[3], vb, pa0, pa1, pa2, pa3);
.LBB0_222:
	v_cmp_neq_f32_e32 vcc, 0, v191
	ds_read_b64_tr_b16 v[174:175], v190 offset:0
	ds_read_b64_tr_b16 v[176:177], v190 offset:0x800
	ds_read_b64_tr_b16 v[206:207], v190 offset:0x1000
	ds_read_b64_tr_b16 v[208:209], v190 offset:0x1800
	s_cbranch_vccnz .LBB0_232
.LBB0_223:
	v_max_f32_e32 v252, v96, v97
	v_max3_f32 v252, v252, v98, v99
	v_max3_f32 v252, v252, v100, v101
	v_max3_f32 v252, v252, v102, v103
	v_max3_f32 v252, v252, v104, v105
	v_max3_f32 v252, v252, v106, v107
	v_max3_f32 v252, v252, v108, v109
	v_max3_f32 v252, v252, v110, v111
	v_max3_f32 v252, v252, v64, v65
	v_max3_f32 v252, v252, v66, v67
	v_max3_f32 v252, v252, v68, v69
	v_max3_f32 v252, v252, v70, v71
	v_max3_f32 v252, v252, v72, v73
	v_max3_f32 v252, v252, v74, v75
	v_max3_f32 v252, v252, v76, v77
	v_max3_f32 v252, v252, v78, v79
	v_mov_b32_e32 v253, v252
	s_nop 1
	v_permlane32_swap_b32_e32 v252, v253
	v_max_f32_e32 v252, v252, v253
	ds_read_b64_tr_b16 v[210:211], v190 offset:0x2000
	ds_read_b64_tr_b16 v[212:213], v190 offset:0x2800
	ds_read_b64_tr_b16 v[214:215], v190 offset:0x3000
	ds_read_b64_tr_b16 v[216:217], v190 offset:0x3800
	s_waitcnt lgkmcnt(4)
	v_mfma_f32_32x32x16_bf16 v[0:15], v[80:83], v[174:177], v[0:15]
	ds_read_b64_tr_b16 v[174:175], v190 offset:0x200
	ds_read_b64_tr_b16 v[176:177], v190 offset:0xa00
	v_mfma_f32_32x32x16_bf16 v[0:15], v[84:87], v[206:209], v[0:15]
	ds_read_b64_tr_b16 v[206:207], v190 offset:0x1200
	ds_read_b64_tr_b16 v[208:209], v190 offset:0x1a00
	s_waitcnt lgkmcnt(4)
	v_mfma_f32_32x32x16_bf16 v[0:15], v[88:91], v[210:213], v[0:15]
	ds_read_b64_tr_b16 v[210:211], v190 offset:0x2200
	ds_read_b64_tr_b16 v[212:213], v190 offset:0x2a00
	v_mfma_f32_32x32x16_bf16 v[0:15], v[92:95], v[214:217], v[0:15]
	ds_read_b64_tr_b16 v[214:215], v190 offset:0x3200
	ds_read_b64_tr_b16 v[216:217], v190 offset:0x3a00
	s_waitcnt lgkmcnt(4)
	v_mfma_f32_32x32x16_bf16 v[48:63], v[80:83], v[174:177], v[48:63]
	ds_read_b64_tr_b16 v[174:175], v190 offset:0x400
	ds_read_b64_tr_b16 v[176:177], v190 offset:0xc00
	v_mfma_f32_32x32x16_bf16 v[48:63], v[84:87], v[206:209], v[48:63]
	ds_read_b64_tr_b16 v[206:207], v190 offset:0x1400
	ds_read_b64_tr_b16 v[208:209], v190 offset:0x1c00
	s_waitcnt lgkmcnt(4)
	v_mfma_f32_32x32x16_bf16 v[48:63], v[88:91], v[210:213], v[48:63]
	ds_read_b64_tr_b16 v[210:211], v190 offset:0x2400
	ds_read_b64_tr_b16 v[212:213], v190 offset:0x2c00
	v_mfma_f32_32x32x16_bf16 v[48:63], v[92:95], v[214:217], v[48:63]
	ds_read_b64_tr_b16 v[214:215], v190 offset:0x3400
	ds_read_b64_tr_b16 v[216:217], v190 offset:0x3c00
	s_waitcnt lgkmcnt(4)
	v_mfma_f32_32x32x16_bf16 v[32:47], v[80:83], v[174:177], v[32:47]
	ds_read_b64_tr_b16 v[174:175], v190 offset:0x600
	ds_read_b64_tr_b16 v[176:177], v190 offset:0xe00
	v_mfma_f32_32x32x16_bf16 v[32:47], v[84:87], v[206:209], v[32:47]
	ds_read_b64_tr_b16 v[206:207], v190 offset:0x1600
	ds_read_b64_tr_b16 v[208:209], v190 offset:0x1e00
	s_waitcnt lgkmcnt(4)
	v_mfma_f32_32x32x16_bf16 v[32:47], v[88:91], v[210:213], v[32:47]
	ds_read_b64_tr_b16 v[210:211], v190 offset:0x2600
	ds_read_b64_tr_b16 v[212:213], v190 offset:0x2e00
	v_mfma_f32_32x32x16_bf16 v[32:47], v[92:95], v[214:217], v[32:47]
	ds_read_b64_tr_b16 v[214:215], v190 offset:0x3600
	ds_read_b64_tr_b16 v[216:217], v190 offset:0x3e00
	s_waitcnt lgkmcnt(4)
	v_mfma_f32_32x32x16_bf16 v[16:31], v[80:83], v[174:177], v[16:31]
	v_mfma_f32_32x32x16_bf16 v[16:31], v[84:87], v[206:209], v[16:31]
	s_waitcnt lgkmcnt(0)
	v_mfma_f32_32x32x16_bf16 v[16:31], v[88:91], v[210:213], v[16:31]
	s_waitcnt vmcnt(3)
	ds_write_b128 v195, v[150:153] offset:49152
	v_mfma_f32_32x32x16_bf16 v[16:31], v[92:95], v[214:217], v[16:31]
	v_cmp_ge_f32_e32 vcc, s45, v252
	s_cmp_eq_u64 vcc, exec
	v_mov_b32_e32 v150, 1.0
	s_cbranch_scc0 .LBB0_233
